# counted lgkmcnt waits for the K-fragment reads of the GQA/context attention QK MFMAs (each MFMA waits only for its own fragment)
# baseline (speedup 1.0000x reference)
.LBB0_567:
	s_lshl_b32 s14, s28, 14
	s_add_i32 s14, s14, 0
	v_add_u32_e32 v1, s14, v129
	v_add_u32_e32 v2, s14, v130
	ds_read_b128 v[52:55], v1
	ds_read_b128 v[56:59], v1 offset:2048
	ds_read_b128 v[60:63], v2
	ds_read_b128 v[64:67], v2 offset:2048
	ds_read_b128 v[68:71], v1 offset:4096
	ds_read_b128 v[72:75], v1 offset:6144
	ds_read_b128 v[76:79], v2 offset:4096
	ds_read_b128 v[80:83], v2 offset:6144
	s_waitcnt lgkmcnt(7)
	v_mfma_f32_16x16x32_bf16 v[84:87], v[52:55], v[4:7], 0
	v_mfma_f32_16x16x32_bf16 v[52:55], v[52:55], v[12:15], 0
	s_waitcnt lgkmcnt(5)
	v_mfma_f32_16x16x32_bf16 v[96:99], v[60:63], v[16:19], v[52:55]
	v_mfma_f32_16x16x32_bf16 v[52:55], v[56:59], v[4:7], 0
	v_mfma_f32_16x16x32_bf16 v[56:59], v[56:59], v[12:15], 0
	s_waitcnt lgkmcnt(4)
	v_mfma_f32_16x16x32_bf16 v[108:111], v[64:67], v[8:11], v[52:55]
	v_mfma_f32_16x16x32_bf16 v[92:95], v[64:67], v[16:19], v[56:59]
	s_waitcnt lgkmcnt(3)
	v_mfma_f32_16x16x32_bf16 v[52:55], v[68:71], v[4:7], 0
	v_mfma_f32_16x16x32_bf16 v[56:59], v[68:71], v[12:15], 0
	s_waitcnt lgkmcnt(1)
	v_mfma_f32_16x16x32_bf16 v[104:107], v[76:79], v[8:11], v[52:55]
	v_mfma_f32_16x16x32_bf16 v[68:71], v[76:79], v[16:19], v[56:59]
	v_mfma_f32_16x16x32_bf16 v[52:55], v[72:75], v[4:7], 0
	v_mfma_f32_16x16x32_bf16 v[56:59], v[72:75], v[12:15], 0
	v_mfma_f32_16x16x32_bf16 v[112:115], v[60:63], v[8:11], v[84:87]
	s_waitcnt lgkmcnt(0)
	v_mfma_f32_16x16x32_bf16 v[100:103], v[80:83], v[8:11], v[52:55]
	v_mfma_f32_16x16x32_bf16 v[56:59], v[80:83], v[16:19], v[56:59]
	v_add_u32_e32 v1, s14, v131
	v_add_u32_e32 v2, s14, v132
	ds_read_b64 v[88:89], v1 offset:8192
	ds_read_b64 v[90:91], v2 offset:8192
	ds_read_b64 v[84:85], v1 offset:10240
	ds_read_b64 v[86:87], v2 offset:10240
	ds_read_b64 v[80:81], v1 offset:12288
	ds_read_b64 v[82:83], v2 offset:12288
	ds_read_b64 v[76:77], v1 offset:14336
	ds_read_b64 v[78:79], v2 offset:14336
	v_add_u32_e32 v1, s14, v133
	v_add_u32_e32 v2, s14, v134
	ds_read_b64 v[72:73], v1 offset:8192
	ds_read_b64 v[74:75], v2 offset:8192
	ds_read_b64 v[64:65], v1 offset:10240
	ds_read_b64 v[66:67], v2 offset:10240
	ds_read_b64 v[60:61], v1 offset:12288
	ds_read_b64 v[62:63], v2 offset:12288
	ds_read_b64 v[52:53], v1 offset:14336
	ds_read_b64 v[54:55], v2 offset:14336
	v_max3_f32 v1, v112, v113, v114
	v_max3_f32 v2, v96, v97, v98
	v_max3_f32 v1, v1, v115, v108
	v_max3_f32 v2, v2, v99, v92
	v_max3_f32 v1, v1, v109, v110
	v_max3_f32 v2, v2, v93, v94
	v_max3_f32 v1, v1, v111, v104
	v_max3_f32 v2, v2, v95, v68
	v_max3_f32 v1, v1, v105, v106
	v_max3_f32 v2, v2, v69, v70
	v_max3_f32 v1, v1, v107, v100
	v_max3_f32 v2, v2, v71, v56
	v_max3_f32 v1, v1, v101, v102
	v_max3_f32 v2, v2, v57, v58
	v_max_f32_e32 v1, v1, v103
	v_max_f32_e32 v2, v2, v59
	v_mov_b32_e32 v3, v1
	v_mov_b32_e32 v138, v2
	s_nop 0
	v_permlane16_swap_b32_e32 v1, v3
	v_permlane16_swap_b32_e32 v2, v138
	v_max_f32_e32 v1, v1, v3
	v_max_f32_e32 v2, v2, v138
	v_mov_b32_e32 v3, v1
	v_mov_b32_e32 v138, v2
	s_nop 0
	v_permlane32_swap_b32_e32 v1, v3
	v_permlane32_swap_b32_e32 v2, v138
	v_max_f32_e32 v1, v1, v3
	v_max_f32_e32 v2, v2, v138
	v_mul_f32_e32 v1, s4, v1
	v_mul_f32_e32 v2, s4, v2
	v_max_f32_e32 v1, v137, v1
	v_max_f32_e32 v2, v136, v2
	v_cmp_gt_f32_e32 vcc, v1, v137
	v_cmp_gt_f32_e64 s[14:15], v2, v136
	s_nop 1
	s_or_b64 s[14:15], vcc, s[14:15]
	s_cbranch_scc0 .Lfa_a_norescale
	v_sub_f32_e32 v138, v137, v1
	v_exp_f32_e32 v138, v138
	v_sub_f32_e32 v3, v136, v2
	v_exp_f32_e32 v3, v3
	v_mul_f32_e32 v135, v135, v138
	v_pk_mul_f32 v[50:51], v[50:51], v[138:139] op_sel_hi:[1,0]
	v_pk_mul_f32 v[48:49], v[48:49], v[138:139] op_sel_hi:[1,0]
	v_pk_mul_f32 v[46:47], v[46:47], v[138:139] op_sel_hi:[1,0]
	v_pk_mul_f32 v[44:45], v[44:45], v[138:139] op_sel_hi:[1,0]
	v_pk_mul_f32 v[42:43], v[42:43], v[138:139] op_sel_hi:[1,0]
	v_pk_mul_f32 v[40:41], v[40:41], v[138:139] op_sel_hi:[1,0]
	v_pk_mul_f32 v[38:39], v[38:39], v[138:139] op_sel_hi:[1,0]
	v_pk_mul_f32 v[36:37], v[36:37], v[138:139] op_sel_hi:[1,0]
	v_mov_b32_e32 v138, v3
	v_mul_f32_e32 v128, v128, v3
	v_pk_mul_f32 v[34:35], v[34:35], v[138:139] op_sel_hi:[1,0]
	v_pk_mul_f32 v[32:33], v[32:33], v[138:139] op_sel_hi:[1,0]
	v_pk_mul_f32 v[30:31], v[30:31], v[138:139] op_sel_hi:[1,0]
	v_pk_mul_f32 v[28:29], v[28:29], v[138:139] op_sel_hi:[1,0]
	v_pk_mul_f32 v[26:27], v[26:27], v[138:139] op_sel_hi:[1,0]
	v_pk_mul_f32 v[24:25], v[24:25], v[138:139] op_sel_hi:[1,0]
	v_pk_mul_f32 v[22:23], v[22:23], v[138:139] op_sel_hi:[1,0]
	v_pk_mul_f32 v[20:21], v[20:21], v[138:139] op_sel_hi:[1,0]
